# S1 also a group rendezvous (P0 stores write-through): all 14 seams group barriers
# speedup vs baseline: 1.0387x; 1.0017x over previous
; __device__ __forceinline__ unsigned pk_bf16(float lo, float hi) { typedef __bf16 b2_t __attribute__((ext_vector_type(2))); f32x2 v = {lo, hi}; b2_t b = __builtin_convertvector(v, b2_t); return __builtin_bit_cast(unsigned, b); }
; #define LAS __attribute__((address_space(3)))
; __device__ __forceinline__ void transpose_tile(const float* W, const float* gain, int K, int N, int k0, int n0, bf16* WT, int drow0, LAS float* scr, int lane) {
;     f32x4 v[8]; float gv[8];
;     const int r0 = lane >> 3, c4 = lane & 7;
; #pragma unroll
;     for (int i = 0; i < 8; ++i) { v[i] = *(const f32x4*)(W + (size_t)(k0 + r0 + 8 * i) * N + n0 + 4 * c4); gv[i] = gain ? gain[k0 + r0 + 8 * i] : 1.0f; }
; #pragma unroll
;     for (int i = 0; i < 8; ++i) { LAS float* d = scr + (r0 + 8 * i) * 33 + 4 * c4; d[0] = v[i][0] * gv[i]; d[1] = v[i][1] * gv[i]; d[2] = v[i][2] * gv[i]; d[3] = v[i][3] * gv[i]; }
;     asm volatile("s_waitcnt lgkmcnt(0)" ::: "memory");
;     const int c = lane & 7;
; #pragma unroll
;     for (int j = 0; j < 4; ++j) { const int n = (lane >> 3) + 8 * j; const LAS float* s = scr + (8 * c) * 33 + n;
;         v4u o; o.x = pk_bf16(s[0 * 33], s[1 * 33]); o.y = pk_bf16(s[2 * 33], s[3 * 33]); o.z = pk_bf16(s[4 * 33], s[5 * 33]); o.w = pk_bf16(s[6 * 33], s[7 * 33]);
;         *(v4u*)(WT + (size_t)(drow0 + n) * K + k0 + 8 * c) = o; }
;     asm volatile("s_waitcnt lgkmcnt(0)" ::: "memory");
; }
; template <bool SWIGLU> __device__ __forceinline__ void transpose_item(const float* W, const float* gain, int K, int N, bf16* WT, LAS float* scr, int item, int lane) {
;     const int nblk = N / 32, kb = item / nblk, nb = item % nblk, n0 = 32 * nb;
;     int drow0 = n0;
;     if (SWIGLU) { const int up = n0 >= FF, f = up ? n0 - FF : n0; drow0 = 256 * (f >> 7) + (up ? 128 : 0) + (f & 127); }
;     transpose_tile(W, gain, K, N, 64 * kb, n0, WT, drow0, scr, lane);
.LBB0_7:
	s_waitcnt vmcnt(7)
	v_pk_mul_f32 v[2:3], v[2:3], v[42:43] op_sel_hi:[1,0]
	ds_write2_b32 v43, v2, v3 offset1:1
	v_pk_mul_f32 v[2:3], v[4:5], v[42:43] op_sel_hi:[1,0]
	ds_write2_b32 v43, v2, v3 offset0:2 offset1:3
	s_waitcnt vmcnt(6)
	v_pk_mul_f32 v[2:3], v[6:7], v[38:39] op_sel_hi:[1,0]
	v_add_u32_e32 v4, 0x420, v43
	ds_write2_b32 v4, v2, v3 offset1:1
	v_pk_mul_f32 v[2:3], v[8:9], v[38:39] op_sel_hi:[1,0]
	v_add_u32_e32 v4, 0x428, v43
	ds_write2_b32 v4, v2, v3 offset1:1
	s_waitcnt vmcnt(5)
	v_pk_mul_f32 v[2:3], v[10:11], v[46:47] op_sel_hi:[1,0]
	v_add_u32_e32 v4, 0x840, v43
	ds_write2_b32 v4, v2, v3 offset1:1
	v_pk_mul_f32 v[2:3], v[12:13], v[46:47] op_sel_hi:[1,0]
	v_add_u32_e32 v4, 0x848, v43
	ds_write2_b32 v4, v2, v3 offset1:1
	s_waitcnt vmcnt(4)
	v_pk_mul_f32 v[2:3], v[14:15], v[40:41] op_sel_hi:[1,0]
	v_add_u32_e32 v4, 0xc60, v43
	ds_write2_b32 v4, v2, v3 offset1:1
	v_pk_mul_f32 v[2:3], v[16:17], v[40:41] op_sel_hi:[1,0]
	v_add_u32_e32 v4, 0xc68, v43
	ds_write2_b32 v4, v2, v3 offset1:1
	s_waitcnt vmcnt(3)
	v_pk_mul_f32 v[2:3], v[18:19], v[52:53] op_sel_hi:[1,0]
	v_add_u32_e32 v4, 0x1080, v43
	ds_write2_b32 v4, v2, v3 offset1:1
	v_pk_mul_f32 v[2:3], v[20:21], v[52:53] op_sel_hi:[1,0]
	v_add_u32_e32 v4, 0x1088, v43
	ds_write2_b32 v4, v2, v3 offset1:1
	s_waitcnt vmcnt(2)
	v_pk_mul_f32 v[2:3], v[22:23], v[44:45] op_sel_hi:[1,0]
	v_add_u32_e32 v4, 0x14a0, v43
	ds_write2_b32 v4, v2, v3 offset1:1
	v_pk_mul_f32 v[2:3], v[24:25], v[44:45] op_sel_hi:[1,0]
	v_add_u32_e32 v4, 0x14a8, v43
	ds_write2_b32 v4, v2, v3 offset1:1
	s_waitcnt vmcnt(1)
	v_pk_mul_f32 v[2:3], v[26:27], v[54:55] op_sel_hi:[1,0]
	v_add_u32_e32 v4, 0x18c0, v43
	s_mulk_i32 s7, 0xff50
	ds_write2_b32 v4, v2, v3 offset1:1
	v_pk_mul_f32 v[2:3], v[28:29], v[54:55] op_sel_hi:[1,0]
	v_add_u32_e32 v4, 0x18c8, v43
	s_add_i32 s2, s18, s7
	s_add_i32 s3, s8, 0xfffff500
	ds_write2_b32 v4, v2, v3 offset1:1
	s_waitcnt vmcnt(0)
	v_pk_mul_f32 v[2:3], v[30:31], v[48:49] op_sel_hi:[1,0]
	v_add_u32_e32 v4, 0x1ce0, v43
	s_cmpk_gt_i32 s2, 0x57
	ds_write2_b32 v4, v2, v3 offset1:1
	v_pk_mul_f32 v[2:3], v[32:33], v[48:49] op_sel_hi:[1,0]
	v_add_u32_e32 v4, 0x1ce8, v43
	s_cselect_b32 s2, s3, s8
	ds_write2_b32 v4, v2, v3 offset1:1
	s_cselect_b32 s3, 0x80, 0
	s_lshl_b32 s7, s2, 1
	s_and_b32 s2, s2, 0x60
	s_waitcnt lgkmcnt(0)
	s_and_b32 s7, s7, 0xffffff00
	s_or_b32 s2, s2, s3
	ds_read2_b32 v[6:7], v41 offset0:33 offset1:41
	ds_read2_b32 v[8:9], v41 offset1:8
	ds_read2_b32 v[10:11], v41 offset0:66 offset1:74
	ds_read2_b32 v[12:13], v41 offset0:99 offset1:107
	ds_read2_b32 v[14:15], v41 offset0:132 offset1:140
	ds_read2_b32 v[16:17], v41 offset0:165 offset1:173
	ds_read2_b32 v[18:19], v41 offset0:198 offset1:206
	ds_read2_b32 v[20:21], v41 offset0:231 offset1:239
	s_or_b32 s2, s2, s7
	v_add_u32_e32 v24, s2, v39
	s_ashr_i32 s7, s6, 31
	v_ashrrev_i32_e32 v25, 31, v24
	v_lshl_add_u64 v[22:23], s[6:7], 1, v[36:37]
	v_lshlrev_b64 v[26:27], 11, v[24:25]
	s_waitcnt lgkmcnt(6)
	v_cvt_pk_bf16_f32 v2, v8, v6
	s_waitcnt lgkmcnt(4)
	v_cvt_pk_bf16_f32 v3, v10, v12
	s_waitcnt lgkmcnt(2)
	v_cvt_pk_bf16_f32 v4, v14, v16
	s_waitcnt lgkmcnt(0)
	v_cvt_pk_bf16_f32 v5, v18, v20
	v_lshl_add_u64 v[26:27], v[22:23], 0, v[26:27]
	v_add_u32_e32 v6, 8, v24
	global_store_dwordx4 v[26:27], v[2:5], off sc1
	s_add_i32 s18, s18, s54
	s_add_i32 s15, s15, s16
	v_cvt_pk_bf16_f32 v2, v9, v7
	v_ashrrev_i32_e32 v7, 31, v6
	v_cvt_pk_bf16_f32 v3, v11, v13
	v_cvt_pk_bf16_f32 v4, v15, v17
	v_cvt_pk_bf16_f32 v5, v19, v21
	v_lshlrev_b64 v[6:7], 11, v[6:7]
	ds_read2_b32 v[8:9], v41 offset0:49 offset1:57
	ds_read2_b32 v[10:11], v41 offset0:16 offset1:24
	ds_read2_b32 v[12:13], v41 offset0:82 offset1:90
	ds_read2_b32 v[14:15], v41 offset0:115 offset1:123
	ds_read2_b32 v[16:17], v41 offset0:148 offset1:156
	ds_read2_b32 v[18:19], v41 offset0:181 offset1:189
	ds_read2_b32 v[20:21], v41 offset0:214 offset1:222
	ds_read2_b32 v[26:27], v41 offset0:247 offset1:255
	v_lshl_add_u64 v[6:7], v[22:23], 0, v[6:7]
	global_store_dwordx4 v[6:7], v[2:5], off sc1
	v_add_u32_e32 v6, 16, v24
	v_ashrrev_i32_e32 v7, 31, v6
	v_lshlrev_b64 v[6:7], 11, v[6:7]
	s_waitcnt lgkmcnt(6)
	v_cvt_pk_bf16_f32 v2, v10, v8
	s_waitcnt lgkmcnt(4)
	v_cvt_pk_bf16_f32 v3, v12, v14
	s_waitcnt lgkmcnt(2)
	v_cvt_pk_bf16_f32 v4, v16, v18
	s_waitcnt lgkmcnt(0)
	v_cvt_pk_bf16_f32 v5, v20, v26
	v_lshl_add_u64 v[6:7], v[22:23], 0, v[6:7]
	global_store_dwordx4 v[6:7], v[2:5], off sc1
	v_add_u32_e32 v6, 24, v24
	v_ashrrev_i32_e32 v7, 31, v6
	v_lshlrev_b64 v[6:7], 11, v[6:7]
	v_cvt_pk_bf16_f32 v2, v11, v9
	v_cvt_pk_bf16_f32 v3, v13, v15
	v_cvt_pk_bf16_f32 v4, v17, v19
	v_cvt_pk_bf16_f32 v5, v21, v27
	v_lshl_add_u64 v[6:7], v[22:23], 0, v[6:7]
	global_store_dwordx4 v[6:7], v[2:5], off sc1
	s_waitcnt lgkmcnt(0)
	s_cmpk_gt_i32 s18, 0xaff
	s_cbranch_scc1 .LBB0_24

; __device__ __forceinline__ unsigned pk_bf16(float lo, float hi) { typedef __bf16 b2_t __attribute__((ext_vector_type(2))); f32x2 v = {lo, hi}; b2_t b = __builtin_convertvector(v, b2_t); return __builtin_bit_cast(unsigned, b); }
; __device__ __forceinline__ void cvt_phase(const float* x, bf16* xn, float* ssq, int gw, int ngw, int lane) {
;     for (int m = gw; m < M; m += ngw) {
;         const f32x4* xr = (const f32x4*)(x + (size_t)m * D) + lane;
;         f32x4 v[4]; float s = 0.f;
; #pragma unroll
;         for (int j = 0; j < 4; ++j) { v[j] = xr[64 * j]; s += (v[j].x * v[j].x + v[j].y * v[j].y) + (v[j].z * v[j].z + v[j].w * v[j].w); }
;         s = wave_sum(s);
;         if (lane == 0) ssq[m] = s;
;         v2u* o = (v2u*)(xn + (size_t)m * D) + lane;
; #pragma unroll
;         for (int j = 0; j < 4; ++j) { v2u w; w.x = pk_bf16(v[j].x, v[j].y); w.y = pk_bf16(v[j].z, v[j].w); o[64 * j] = w; }
;     }
.LBB0_26:
	s_or_b64 exec, exec, s[12:13]
	s_waitcnt lgkmcnt(0)
	v_lshl_add_u64 v[30:31], s[44:45], 0, v[18:19]
	v_cvt_pk_bf16_f32 v6, v6, v7
	v_cvt_pk_bf16_f32 v7, v8, v9
	v_add_co_u32_e32 v8, vcc, 0x5400000, v30
	s_add_i32 s18, s18, s54
	s_nop 0
	v_addc_co_u32_e32 v9, vcc, 0, v31, vcc
	v_cvt_pk_bf16_f32 v2, v2, v3
	v_cvt_pk_bf16_f32 v3, v4, v5
	s_add_u32 s16, s16, s6
	global_store_dwordx2 v[8:9], v[2:3], off offset:512 sc1
	v_cvt_pk_bf16_f32 v2, v10, v11
	v_cvt_pk_bf16_f32 v3, v12, v13
	s_addc_u32 s17, s17, s7
	global_store_dwordx2 v[8:9], v[2:3], off offset:1024 sc1
	v_cvt_pk_bf16_f32 v2, v14, v15
	v_cvt_pk_bf16_f32 v3, v16, v17
	v_lshl_add_u64 v[18:19], v[18:19], 0, s[8:9]
	s_cmpk_lt_i32 s18, 0x4000
	v_lshl_add_u64 v[22:23], v[22:23], 0, s[10:11]
	global_store_dwordx2 v[8:9], v[6:7], off sc1
	global_store_dwordx2 v[8:9], v[2:3], off offset:1536 sc1
	s_cbranch_scc0 .LBB0_29
.LBB0_27:
	global_load_dwordx4 v[6:9], v[22:23], off offset:-3072 nt
	global_load_dwordx4 v[2:5], v[22:23], off offset:-2048 nt
	global_load_dwordx4 v[10:13], v[22:23], off offset:-1024 nt
	global_load_dwordx4 v[14:17], v[22:23], off nt
	s_waitcnt vmcnt(3)
	v_mul_f32_e32 v20, v7, v7
	v_mul_f32_e32 v30, v9, v9
	s_waitcnt vmcnt(2)
	v_mul_f32_e32 v31, v3, v3
	v_mul_f32_e32 v32, v5, v5
	s_waitcnt vmcnt(1)
	v_mul_f32_e32 v33, v11, v11
	v_mul_f32_e32 v34, v13, v13
	v_fmac_f32_e32 v20, v6, v6
	v_fmac_f32_e32 v30, v8, v8
	v_fmac_f32_e32 v31, v2, v2
	v_fmac_f32_e32 v32, v4, v4
	s_waitcnt vmcnt(0)
	v_mul_f32_e32 v35, v15, v15
	v_mul_f32_e32 v36, v17, v17
	v_fmac_f32_e32 v33, v10, v10
	v_fmac_f32_e32 v34, v12, v12
	v_add_f32_e32 v20, v20, v30
	v_add_f32_e32 v30, v31, v32
	v_fmac_f32_e32 v35, v14, v14
	v_fmac_f32_e32 v36, v16, v16
	v_add_f32_e32 v31, v33, v34
	v_add_f32_e32 v20, v20, v30
	v_add_f32_e32 v20, v20, v31
	v_add_f32_e32 v30, v35, v36
	v_add_f32_e32 v20, v20, v30
	ds_bpermute_b32 v30, v24, v20
	s_waitcnt lgkmcnt(0)
	v_add_f32_e32 v20, v20, v30
	ds_bpermute_b32 v30, v25, v20
	s_waitcnt lgkmcnt(0)
	v_add_f32_e32 v20, v20, v30
	ds_bpermute_b32 v30, v26, v20
	s_waitcnt lgkmcnt(0)
	v_add_f32_e32 v20, v20, v30
	ds_bpermute_b32 v30, v27, v20
	s_waitcnt lgkmcnt(0)
	v_add_f32_e32 v20, v20, v30
	ds_bpermute_b32 v30, v28, v20
	s_waitcnt lgkmcnt(0)
	v_add_f32_e32 v20, v20, v30
	ds_bpermute_b32 v30, v29, v20
	s_and_saveexec_b64 s[12:13], s[2:3]
	s_cbranch_execz .LBB0_26
	s_add_u32 s20, s44, s16
	s_waitcnt lgkmcnt(0)
	v_add_f32_e32 v20, v20, v30
	s_addc_u32 s21, s45, s17
	global_store_dword v21, v20, s[20:21] sc1
	s_branch .LBB0_26

; __global__ void __launch_bounds__(512, 2) fwd_megakernel(Args a) {
;     ...
;         for (int i = bid * 512 + tid; i < 2 * BATCH * NCH * D; i += G * 512) ((unsigned long long*)(ws + WS_SUM))[i] = 0ull;
.LBB0_31:
	v_add_u32_e32 v2, s6, v2
	v_cmp_lt_i32_e32 vcc, s7, v2
	global_store_dwordx2 v[4:5], v[6:7], off sc1
	s_or_b64 s[10:11], vcc, s[10:11]
	v_lshl_add_u64 v[4:5], v[4:5], 0, s[8:9]
	s_andn2_b64 exec, exec, s[10:11]
	s_cbranch_execnz .LBB0_31

; __device__ __forceinline__ int lane_id_() { int l; asm volatile("v_mbcnt_lo_u32_b32 %0, -1, 0\n\tv_mbcnt_hi_u32_b32 %0, -1, %0" : "=v"(l)); return l; }
; __device__ __forceinline__ unsigned xb_ld(unsigned* p)              { return __hip_atomic_load(p, __ATOMIC_RELAXED, __HIP_MEMORY_SCOPE_AGENT); }
; __device__ __forceinline__ unsigned xb_add(unsigned* p, unsigned v) { return __hip_atomic_fetch_add(p, v, __ATOMIC_RELAXED, __HIP_MEMORY_SCOPE_AGENT); }
; #define XB_SPIN(cond, bar) do { unsigned _sp = 0; while (cond) { __builtin_amdgcn_s_sleep(1); \
;     if ((++_sp & 255u) == 0u) { if (xb_ld(&(bar)[XB_TMO])) break; if (_sp > XB_SPIN_CAP) { atomicAdd(&(bar)[XB_TMO], 1u); break; } } } } while (0)
; #define SEAM() xcd_barrier(xbar, wave)
; __device__ __forceinline__ void xcd_barrier(const XcdBarrier& b, int wave_s) {
;     asm volatile("s_waitcnt vmcnt(0)" ::: "memory");
;     __syncthreads();
;     if (wave_s == 0 && lane_id_() == 0) {
;         unsigned* bar = b.bar;
;         __builtin_amdgcn_s_waitcnt(0);
;         unsigned nloc = b.st[0], nx = b.st[1];
;         if (nloc == 0u) { xcd_barrier_complete(bar, b.x, nloc, nx); b.st[0] = nloc; b.st[1] = nx; }
;         const unsigned old = xb_add(&bar[XB_XSUB(b.x)], 1u);
;         const unsigned gen = old / nloc;
;         if (old + 1u == (gen + 1u) * nloc) {
;             __builtin_amdgcn_fence(__ATOMIC_RELEASE, "agent");
;             asm volatile("s_waitcnt vmcnt(0)" ::: "memory");
;             const unsigned og = xb_add(&bar[XB_TOP], 1u);
;             const unsigned tg = og / nx;
;             if (og + 1u == (tg + 1u) * nx) xb_add(&bar[XB_TOPGEN], 1u);
;             else XB_SPIN(xb_ld(&bar[XB_TOPGEN]) == tg, bar);
;             __builtin_amdgcn_fence(__ATOMIC_ACQUIRE, "agent");
;             xb_add(&bar[XB_XGEN(b.x)], 1u);
;             asm volatile("s_waitcnt vmcnt(0)" ::: "memory");
;         } else {
;             XB_SPIN(xb_ld(&bar[XB_XGEN(b.x)]) == gen, bar);
;             __builtin_amdgcn_fence(__ATOMIC_ACQUIRE, "agent");
;             asm volatile("s_waitcnt vmcnt(0)" ::: "memory");
;         }
;     }
;     __syncthreads();
; }
; __global__ void __launch_bounds__(512, 2) fwd_megakernel(Args a) {
;     ...
;     if (a.ws == nullptr) grid.sync();
;     SEAM();
.LBB0_44:
	s_waitcnt vmcnt(0)
	s_cmp_lt_u32 s83, 64
	s_cselect_b64 s[4:5], -1, 0
	s_cmp_gt_u32 s83, 63
	s_barrier
	s_cbranch_scc1 .LBB0_98
	v_mbcnt_lo_u32_b32 v0, -1, 0
	v_mbcnt_hi_u32_b32 v0, -1, v0
	s_nop 0
	v_cmp_eq_u32_e32 vcc, 0, v0
	s_and_saveexec_b64 s[2:3], vcc
	s_cbranch_execz .LBB0_97
	s_cmpk_eq_u32 s46, 0x100
	s_cbranch_scc0 .Lglob_S1
	s_and_b32 s98, s33, 7
	s_lshl_b32 s99, s98, 2
	s_addk_i32 s99, 0x4800
	v_mov_b32_e32 v3, s99
	s_lshl_b32 s98, s98, 8
	s_addk_i32 s98, 0x4000
	v_mov_b32_e32 v0, s98
	v_mov_b32_e32 v1, 1
	global_atomic_add v2, v0, v1, s[44:45] sc0
	buffer_inv sc1
	s_waitcnt vmcnt(1)
	v_readfirstlane_b32 s98, v2
	s_nop 3
	s_add_u32 s99, s98, 1
	s_and_b32 s99, s99, 31
	s_lshr_b32 s98, s98, 5
	s_cmp_eq_u32 s99, 0
	s_cbranch_scc0 .Llw_S1
	global_atomic_add v3, v1, s[44:45]
	s_branch .Lrvp_S1
